# P2 K-loop: 12 of the 16 LDS-DMA loads per loop body use SGPR pointer + 32-bit lane offset (saddr form); the 64-bit VALU address adds for them are gone
# baseline (speedup 1.0000x reference)
.LBB0_202:
	ds_read_b128 v[52:55], v171
	ds_read_b128 v[60:63], v171 offset:1024
	ds_read_b128 v[64:67], v171 offset:2048
	ds_read_b128 v[72:75], v171 offset:3072
	ds_read_b128 v[164:167], v172
	ds_read_b128 v[176:179], v172 offset:1024
	ds_read_b128 v[180:183], v172 offset:2048
	ds_read_b128 v[184:187], v172 offset:3072
	s_add_u32 s30, s28, 0xfff80080
	s_addc_u32 s31, s29, -1
	s_cmp_eq_u32 s75, 28
	s_cselect_b32 s35, s5, s31
	s_cselect_b32 s34, s21, s30
	s_cselect_b32 s31, s19, s74
	s_cselect_b32 s30, s72, s73
	s_add_u32 s100, s30, 0x80
	s_addc_u32 s101, s31, 0
	s_add_i32 m0, s27, 0xc000
	ds_read_b128 v[188:191], v173
	ds_read_b128 v[194:197], v173 offset:1024
	ds_read_b128 v[198:201], v173 offset:2048
	ds_read_b128 v[202:205], v173 offset:3072
	ds_read_b128 v[206:209], v173 offset:4096
	ds_read_b128 v[210:213], v173 offset:5120
	ds_read_b128 v[214:217], v173 offset:6144
	ds_read_b128 v[218:221], v173 offset:7168
	global_load_lds_dwordx4 v156, s[28:29]
	s_add_i32 m0, s27, 0xe000
	s_nop 0
	global_load_lds_dwordx4 v158, s[28:29]
	s_waitcnt vmcnt(8)
	s_waitcnt lgkmcnt(0)
	s_barrier
	s_setprio 1
	s_waitcnt lgkmcnt(0)
	v_mfma_f32_16x16x32_bf16 v[140:143], v[52:55], v[188:191], v[140:143]
	v_mfma_f32_16x16x32_bf16 v[136:139], v[64:67], v[188:191], v[136:139]
	v_mfma_f32_16x16x32_bf16 v[124:127], v[52:55], v[198:201], v[124:127]
	v_mfma_f32_16x16x32_bf16 v[120:123], v[64:67], v[198:201], v[120:123]
	v_mfma_f32_16x16x32_bf16 v[108:111], v[52:55], v[206:209], v[108:111]
	v_mfma_f32_16x16x32_bf16 v[104:107], v[64:67], v[206:209], v[104:107]
	v_mfma_f32_16x16x32_bf16 v[92:95], v[52:55], v[214:217], v[92:95]
	v_mfma_f32_16x16x32_bf16 v[88:91], v[64:67], v[214:217], v[88:91]
	v_mfma_f32_16x16x32_bf16 v[140:143], v[60:63], v[194:197], v[140:143]
	v_mfma_f32_16x16x32_bf16 v[136:139], v[72:75], v[194:197], v[136:139]
	v_mfma_f32_16x16x32_bf16 v[124:127], v[60:63], v[202:205], v[124:127]
	v_mfma_f32_16x16x32_bf16 v[120:123], v[72:75], v[202:205], v[120:123]
	v_mfma_f32_16x16x32_bf16 v[108:111], v[60:63], v[210:213], v[108:111]
	v_mfma_f32_16x16x32_bf16 v[104:107], v[72:75], v[210:213], v[104:107]
	v_mfma_f32_16x16x32_bf16 v[92:95], v[60:63], v[218:221], v[92:95]
	v_mfma_f32_16x16x32_bf16 v[88:91], v[72:75], v[218:221], v[88:91]
	s_setprio 0
	s_setprio 1
	v_mfma_f32_16x16x32_bf16 v[132:135], v[164:167], v[188:191], v[132:135]
	v_mfma_f32_16x16x32_bf16 v[128:131], v[180:183], v[188:191], v[128:131]
	v_mfma_f32_16x16x32_bf16 v[116:119], v[164:167], v[198:201], v[116:119]
	v_mfma_f32_16x16x32_bf16 v[112:115], v[180:183], v[198:201], v[112:115]
	v_mfma_f32_16x16x32_bf16 v[100:103], v[164:167], v[206:209], v[100:103]
	v_mfma_f32_16x16x32_bf16 v[96:99], v[180:183], v[206:209], v[96:99]
	v_mfma_f32_16x16x32_bf16 v[84:87], v[164:167], v[214:217], v[84:87]
	v_mfma_f32_16x16x32_bf16 v[80:83], v[180:183], v[214:217], v[80:83]
	v_mfma_f32_16x16x32_bf16 v[132:135], v[176:179], v[194:197], v[132:135]
	v_mfma_f32_16x16x32_bf16 v[128:131], v[184:187], v[194:197], v[128:131]
	v_mfma_f32_16x16x32_bf16 v[116:119], v[176:179], v[202:205], v[116:119]
	v_mfma_f32_16x16x32_bf16 v[112:115], v[184:187], v[202:205], v[112:115]
	v_mfma_f32_16x16x32_bf16 v[100:103], v[176:179], v[210:213], v[100:103]
	v_mfma_f32_16x16x32_bf16 v[96:99], v[184:187], v[210:213], v[96:99]
	v_mfma_f32_16x16x32_bf16 v[84:87], v[176:179], v[218:221], v[84:87]
	v_mfma_f32_16x16x32_bf16 v[80:83], v[184:187], v[218:221], v[80:83]
	s_setprio 0
	s_barrier
	s_add_i32 s76, s69, s38
	s_mov_b32 m0, s76
	ds_read_b128 v[188:191], v173 offset:16384
	ds_read_b128 v[194:197], v173 offset:17408
	ds_read_b128 v[198:201], v173 offset:18432
	ds_read_b128 v[202:205], v173 offset:19456
	ds_read_b128 v[206:209], v173 offset:20480
	ds_read_b128 v[210:213], v173 offset:21504
	ds_read_b128 v[214:217], v173 offset:22528
	ds_read_b128 v[218:221], v173 offset:23552
	global_load_lds_dwordx4 v150, s[30:31]
	s_add_i32 m0, s76, 0x2000
	s_add_u32 s76, s30, 0x80000
	s_addc_u32 s77, s31, 0
	s_add_i32 s84, s70, s38
	global_load_lds_dwordx4 v154, s[30:31]
	s_mov_b32 m0, s84
	v_lshl_add_u64 v[226:227], s[34:35], 0, v[152:153]
	global_load_lds_dwordx4 v150, s[76:77]
	s_add_i32 m0, s84, 0x2000
	s_nop 0
	global_load_lds_dwordx4 v154, s[76:77]
	v_lshl_add_u64 v[224:225], s[34:35], 0, v[148:149]
	s_mov_b32 m0, s27
	s_nop 0
	global_load_lds_dwordx4 v[224:225], off
	s_mov_b32 m0, s39
	s_nop 0
	global_load_lds_dwordx4 v[226:227], off
	s_waitcnt vmcnt(8)
	s_waitcnt lgkmcnt(0)
	s_barrier
	s_setprio 1
	s_waitcnt lgkmcnt(0)
	v_mfma_f32_16x16x32_bf16 v[76:79], v[52:55], v[188:191], v[76:79]
	v_mfma_f32_16x16x32_bf16 v[68:71], v[64:67], v[188:191], v[68:71]
	v_mfma_f32_16x16x32_bf16 v[44:47], v[52:55], v[198:201], v[44:47]
	v_mfma_f32_16x16x32_bf16 v[40:43], v[64:67], v[198:201], v[40:43]
	v_mfma_f32_16x16x32_bf16 v[28:31], v[52:55], v[206:209], v[28:31]
	v_mfma_f32_16x16x32_bf16 v[24:27], v[64:67], v[206:209], v[24:27]
	v_mfma_f32_16x16x32_bf16 v[12:15], v[52:55], v[214:217], v[12:15]
	v_mfma_f32_16x16x32_bf16 v[8:11], v[64:67], v[214:217], v[8:11]
	v_mfma_f32_16x16x32_bf16 v[76:79], v[60:63], v[194:197], v[76:79]
	v_mfma_f32_16x16x32_bf16 v[68:71], v[72:75], v[194:197], v[68:71]
	v_mfma_f32_16x16x32_bf16 v[44:47], v[60:63], v[202:205], v[44:47]
	v_mfma_f32_16x16x32_bf16 v[40:43], v[72:75], v[202:205], v[40:43]
	v_mfma_f32_16x16x32_bf16 v[28:31], v[60:63], v[210:213], v[28:31]
	v_mfma_f32_16x16x32_bf16 v[24:27], v[72:75], v[210:213], v[24:27]
	v_mfma_f32_16x16x32_bf16 v[12:15], v[60:63], v[218:221], v[12:15]
	v_mfma_f32_16x16x32_bf16 v[8:11], v[72:75], v[218:221], v[8:11]
	s_setprio 0
	s_setprio 1
	v_mfma_f32_16x16x32_bf16 v[48:51], v[180:183], v[188:191], v[48:51]
	v_mfma_f32_16x16x32_bf16 v[36:39], v[164:167], v[198:201], v[36:39]
	v_mfma_f32_16x16x32_bf16 v[32:35], v[180:183], v[198:201], v[32:35]
	v_mfma_f32_16x16x32_bf16 v[20:23], v[164:167], v[206:209], v[20:23]
	v_mfma_f32_16x16x32_bf16 v[16:19], v[180:183], v[206:209], v[16:19]
	v_mfma_f32_16x16x32_bf16 v[4:7], v[164:167], v[214:217], v[4:7]
	v_mfma_f32_16x16x32_bf16 v[0:3], v[180:183], v[214:217], v[0:3]
	v_mfma_f32_16x16x32_bf16 v[52:55], v[164:167], v[188:191], v[56:59]
	v_mfma_f32_16x16x32_bf16 v[48:51], v[184:187], v[194:197], v[48:51]
	v_mfma_f32_16x16x32_bf16 v[36:39], v[176:179], v[202:205], v[36:39]
	v_mfma_f32_16x16x32_bf16 v[32:35], v[184:187], v[202:205], v[32:35]
	v_mfma_f32_16x16x32_bf16 v[20:23], v[176:179], v[210:213], v[20:23]
	v_mfma_f32_16x16x32_bf16 v[16:19], v[184:187], v[210:213], v[16:19]
	v_mfma_f32_16x16x32_bf16 v[4:7], v[176:179], v[218:221], v[4:7]
	v_mfma_f32_16x16x32_bf16 v[0:3], v[184:187], v[218:221], v[0:3]
	v_mfma_f32_16x16x32_bf16 v[52:55], v[176:179], v[194:197], v[52:55]
	s_setprio 0
	s_barrier
	s_add_i32 s76, 0, 0x18000
	s_add_i32 s77, 0, 0x1c000
	v_add_u32_e32 v72, s76, v170
	v_add_u32_e32 v175, s77, v170
	ds_read_b128 v[56:59], v72
	ds_read_b128 v[60:63], v72 offset:1024
	ds_read_b128 v[64:67], v72 offset:2048
	ds_read_b128 v[72:75], v72 offset:3072
	ds_read_b128 v[164:167], v175
	ds_read_b128 v[176:179], v175 offset:1024
	ds_read_b128 v[180:183], v175 offset:2048
	ds_read_b128 v[184:187], v175 offset:3072
	s_add_u32 s34, s34, 0x80000
	s_addc_u32 s35, s35, 0
	s_mov_b32 m0, s40
	ds_read_b128 v[188:191], v173 offset:32768
	ds_read_b128 v[194:197], v173 offset:33792
	ds_read_b128 v[198:201], v173 offset:34816
	ds_read_b128 v[202:205], v173 offset:35840
	ds_read_b128 v[206:209], v173 offset:36864
	ds_read_b128 v[210:213], v173 offset:37888
	ds_read_b128 v[214:217], v173 offset:38912
	ds_read_b128 v[218:221], v173 offset:39936
	global_load_lds_dwordx4 v148, s[34:35]
	s_mov_b32 m0, s41
	s_nop 0
	global_load_lds_dwordx4 v152, s[34:35]
	s_waitcnt vmcnt(8)
	s_waitcnt lgkmcnt(0)
	s_barrier
	s_setprio 1
	s_waitcnt lgkmcnt(0)
	v_mfma_f32_16x16x32_bf16 v[140:143], v[56:59], v[188:191], v[140:143]
	v_mfma_f32_16x16x32_bf16 v[136:139], v[64:67], v[188:191], v[136:139]
	v_mfma_f32_16x16x32_bf16 v[124:127], v[56:59], v[198:201], v[124:127]
	v_mfma_f32_16x16x32_bf16 v[120:123], v[64:67], v[198:201], v[120:123]
	v_mfma_f32_16x16x32_bf16 v[108:111], v[56:59], v[206:209], v[108:111]
	v_mfma_f32_16x16x32_bf16 v[104:107], v[64:67], v[206:209], v[104:107]
	v_mfma_f32_16x16x32_bf16 v[92:95], v[56:59], v[214:217], v[92:95]
	v_mfma_f32_16x16x32_bf16 v[88:91], v[64:67], v[214:217], v[88:91]
	v_mfma_f32_16x16x32_bf16 v[140:143], v[60:63], v[194:197], v[140:143]
	v_mfma_f32_16x16x32_bf16 v[136:139], v[72:75], v[194:197], v[136:139]
	v_mfma_f32_16x16x32_bf16 v[124:127], v[60:63], v[202:205], v[124:127]
	v_mfma_f32_16x16x32_bf16 v[120:123], v[72:75], v[202:205], v[120:123]
	v_mfma_f32_16x16x32_bf16 v[108:111], v[60:63], v[210:213], v[108:111]
	v_mfma_f32_16x16x32_bf16 v[104:107], v[72:75], v[210:213], v[104:107]
	v_mfma_f32_16x16x32_bf16 v[92:95], v[60:63], v[218:221], v[92:95]
	v_mfma_f32_16x16x32_bf16 v[88:91], v[72:75], v[218:221], v[88:91]
	s_setprio 0
	s_setprio 1
	v_mfma_f32_16x16x32_bf16 v[132:135], v[164:167], v[188:191], v[132:135]
	v_mfma_f32_16x16x32_bf16 v[128:131], v[180:183], v[188:191], v[128:131]
	v_mfma_f32_16x16x32_bf16 v[116:119], v[164:167], v[198:201], v[116:119]
	v_mfma_f32_16x16x32_bf16 v[112:115], v[180:183], v[198:201], v[112:115]
	v_mfma_f32_16x16x32_bf16 v[100:103], v[164:167], v[206:209], v[100:103]
	v_mfma_f32_16x16x32_bf16 v[96:99], v[180:183], v[206:209], v[96:99]
	v_mfma_f32_16x16x32_bf16 v[84:87], v[164:167], v[214:217], v[84:87]
	v_mfma_f32_16x16x32_bf16 v[80:83], v[180:183], v[214:217], v[80:83]
	v_mfma_f32_16x16x32_bf16 v[132:135], v[176:179], v[194:197], v[132:135]
	v_mfma_f32_16x16x32_bf16 v[128:131], v[184:187], v[194:197], v[128:131]
	v_mfma_f32_16x16x32_bf16 v[116:119], v[176:179], v[202:205], v[116:119]
	v_mfma_f32_16x16x32_bf16 v[112:115], v[184:187], v[202:205], v[112:115]
	v_mfma_f32_16x16x32_bf16 v[100:103], v[176:179], v[210:213], v[100:103]
	v_mfma_f32_16x16x32_bf16 v[96:99], v[184:187], v[210:213], v[96:99]
	v_mfma_f32_16x16x32_bf16 v[84:87], v[176:179], v[218:221], v[84:87]
	v_mfma_f32_16x16x32_bf16 v[80:83], v[184:187], v[218:221], v[80:83]
	s_setprio 0
	s_barrier
	s_add_i32 s34, s76, s38
	s_mov_b32 m0, s34
	ds_read_b128 v[188:191], v173 offset:49152
	ds_read_b128 v[194:197], v173 offset:50176
	ds_read_b128 v[198:201], v173 offset:51200
	ds_read_b128 v[202:205], v173 offset:52224
	ds_read_b128 v[206:209], v173 offset:53248
	ds_read_b128 v[210:213], v173 offset:54272
	ds_read_b128 v[214:217], v173 offset:55296
	ds_read_b128 v[218:221], v173 offset:56320
	global_load_lds_dwordx4 v150, s[100:101]
	s_add_i32 m0, s34, 0x2000
	s_add_u32 s30, s30, 0x80080
	s_addc_u32 s31, s31, 0
	s_add_i32 s34, s77, s38
	global_load_lds_dwordx4 v154, s[100:101]
	s_mov_b32 m0, s34
	s_nop 0
	global_load_lds_dwordx4 v150, s[30:31]
	s_add_i32 m0, s34, 0x2000
	s_nop 0
	global_load_lds_dwordx4 v154, s[30:31]
	v_lshl_add_u64 v[168:169], v[224:225], 0, s[14:15]
	s_mov_b32 m0, s57
	s_nop 0
	global_load_lds_dwordx4 v[168:169], off
	v_lshl_add_u64 v[168:169], v[226:227], 0, s[14:15]
	s_mov_b32 m0, s66
	s_nop 0
	global_load_lds_dwordx4 v[168:169], off
	s_waitcnt vmcnt(8)
	s_waitcnt lgkmcnt(0)
	s_barrier
	s_setprio 1
	s_waitcnt lgkmcnt(0)
	v_mfma_f32_16x16x32_bf16 v[76:79], v[56:59], v[188:191], v[76:79]
	v_mfma_f32_16x16x32_bf16 v[68:71], v[64:67], v[188:191], v[68:71]
	v_mfma_f32_16x16x32_bf16 v[44:47], v[56:59], v[198:201], v[44:47]
	v_mfma_f32_16x16x32_bf16 v[40:43], v[64:67], v[198:201], v[40:43]
	v_mfma_f32_16x16x32_bf16 v[28:31], v[56:59], v[206:209], v[28:31]
	v_mfma_f32_16x16x32_bf16 v[24:27], v[64:67], v[206:209], v[24:27]
	v_mfma_f32_16x16x32_bf16 v[12:15], v[56:59], v[214:217], v[12:15]
	v_mfma_f32_16x16x32_bf16 v[8:11], v[64:67], v[214:217], v[8:11]
	v_mfma_f32_16x16x32_bf16 v[76:79], v[60:63], v[194:197], v[76:79]
	v_mfma_f32_16x16x32_bf16 v[68:71], v[72:75], v[194:197], v[68:71]
	v_mfma_f32_16x16x32_bf16 v[44:47], v[60:63], v[202:205], v[44:47]
	v_mfma_f32_16x16x32_bf16 v[40:43], v[72:75], v[202:205], v[40:43]
	v_mfma_f32_16x16x32_bf16 v[28:31], v[60:63], v[210:213], v[28:31]
	v_mfma_f32_16x16x32_bf16 v[24:27], v[72:75], v[210:213], v[24:27]
	v_mfma_f32_16x16x32_bf16 v[12:15], v[60:63], v[218:221], v[12:15]
	v_mfma_f32_16x16x32_bf16 v[8:11], v[72:75], v[218:221], v[8:11]
	s_setprio 0
	s_setprio 1
	v_mfma_f32_16x16x32_bf16 v[52:55], v[164:167], v[188:191], v[52:55]
	v_mfma_f32_16x16x32_bf16 v[48:51], v[180:183], v[188:191], v[48:51]
	v_mfma_f32_16x16x32_bf16 v[36:39], v[164:167], v[198:201], v[36:39]
	v_mfma_f32_16x16x32_bf16 v[32:35], v[180:183], v[198:201], v[32:35]
	v_mfma_f32_16x16x32_bf16 v[20:23], v[164:167], v[206:209], v[20:23]
	v_mfma_f32_16x16x32_bf16 v[16:19], v[180:183], v[206:209], v[16:19]
	v_mfma_f32_16x16x32_bf16 v[4:7], v[164:167], v[214:217], v[4:7]
	v_mfma_f32_16x16x32_bf16 v[0:3], v[180:183], v[214:217], v[0:3]
	v_mfma_f32_16x16x32_bf16 v[56:59], v[176:179], v[194:197], v[52:55]
	v_mfma_f32_16x16x32_bf16 v[48:51], v[184:187], v[194:197], v[48:51]
	v_mfma_f32_16x16x32_bf16 v[36:39], v[176:179], v[202:205], v[36:39]
	v_mfma_f32_16x16x32_bf16 v[32:35], v[184:187], v[202:205], v[32:35]
	v_mfma_f32_16x16x32_bf16 v[20:23], v[176:179], v[210:213], v[20:23]
	v_mfma_f32_16x16x32_bf16 v[16:19], v[184:187], v[210:213], v[16:19]
	v_mfma_f32_16x16x32_bf16 v[4:7], v[176:179], v[218:221], v[4:7]
	v_mfma_f32_16x16x32_bf16 v[0:3], v[184:187], v[218:221], v[0:3]
	s_setprio 0
	s_barrier
	s_add_i32 s75, s75, 2
	s_add_u32 s28, s28, 0x100
	s_addc_u32 s29, s29, 0
	s_add_u32 s73, s73, 0x100
	s_addc_u32 s74, s74, 0
	s_cmp_gt_u32 s75, 29
	s_cbranch_scc0 .LBB0_202
	s_and_b64 vcc, exec, s[16:17]
	s_cbranch_vccz .LBB0_205
	s_barrier

.LBB0_522:
	s_nop 0
	s_nop 0
	s_nop 0
	s_nop 0
	s_nop 0
	s_nop 0
	s_nop 0
	s_nop 0
	s_nop 0
	s_nop 0
	s_nop 0
	s_nop 0
	s_nop 0
	s_cmp_lt_i32 s80, 7
	s_cselect_b64 s[0:1], -1, 0
	s_cmp_gt_i32 s81, 6
	s_cselect_b64 s[4:5], -1, 0
	s_and_b64 s[0:1], s[0:1], s[4:5]
	s_andn2_b64 vcc, exec, s[0:1]
	s_cbranch_vccnz .LBB0_622
	v_lshrrev_b32_e32 v2, 1, v144
	v_lshrrev_b32_e32 v3, 5, v144
	v_and_b32_e32 v2, 24, v2
	v_and_b32_e32 v3, 4, v3
	v_bfe_u32 v4, v144, 2, 2
	v_lshlrev_b32_e32 v0, 4, v144
	v_and_b32_e32 v1, 32, v144
	v_bfe_u32 v10, v144, 2, 4
	v_or3_b32 v2, v3, v4, v2
	v_lshrrev_b32_e32 v3, 3, v144
	s_movk_i32 s0, 0x70
	v_bitop3_b32 v8, v0, v1, 48 bitop3:0x6c
	v_and_b32_e32 v9, 64, v144
	v_and_or_b32 v4, v3, s0, v10
	s_movk_i32 s0, 0x60
	v_add_u32_e32 v11, 0x2000, v0
	v_or_b32_e32 v1, v8, v9
	v_and_or_b32 v3, v3, s0, v2
	v_lshrrev_b32_e32 v0, 7, v11
	s_movk_i32 s0, 0xf0
	s_add_u32 s30, s62, 0x4000000
	v_lshl_or_b32 v150, v4, 12, v1
	v_and_or_b32 v3, v0, s0, v10
	s_movk_i32 s0, 0xe0
	s_addc_u32 s31, s63, 0
	v_and_or_b32 v0, v0, s0, v2
	s_lshl_b32 s0, s2, 2
	s_and_b32 s0, s0, 28
	s_ashr_i32 s1, s2, 6
	s_add_i32 s0, s0, s1
	s_waitcnt lgkmcnt(0)
	s_bfe_u32 s16, s2, 0x30003
	s_ashr_i32 s1, s0, 31
	s_lshl_b64 s[6:7], s[0:1], 20
	s_lshl_b32 s2, s16, 20
	s_add_u32 s1, s62, s2
	s_addc_u32 s3, s63, 0
	s_add_u32 s4, s1, 0x1200000
	s_addc_u32 s5, s3, 0
	s_add_u32 s8, s1, 0x1280000
	s_addc_u32 s9, s3, 0
	s_add_u32 s6, s30, s6
	s_addc_u32 s7, s31, s7
	s_add_u32 s10, s6, 0x80000
	v_readfirstlane_b32 s3, v144
	s_addc_u32 s11, s7, 0
	s_lshr_b32 s18, s3, 6
	s_lshl_b32 s1, s18, 10
	s_add_i32 s34, s1, 0
	s_add_i32 m0, s34, 0x10000
	v_lshl_or_b32 v154, v3, 12, v1
	global_load_lds_dwordx4 v150, s[4:5]
	s_add_i32 m0, s34, 0x12000
	v_lshl_or_b32 v148, v4, 12, v1
	global_load_lds_dwordx4 v154, s[4:5]
	s_add_i32 m0, s34, 0x14000
	s_add_i32 s35, s34, 0x2000
	global_load_lds_dwordx4 v150, s[8:9]
	s_add_i32 m0, s34, 0x16000
	v_lshl_or_b32 v152, v3, 12, v1
	global_load_lds_dwordx4 v154, s[8:9]
	s_mov_b32 m0, s34
	s_add_i32 s36, s34, 0x4000
	global_load_lds_dwordx4 v148, s[6:7]
	s_mov_b32 m0, s35
	s_add_i32 s37, s34, 0x6000
	global_load_lds_dwordx4 v152, s[6:7]
	s_mov_b32 m0, s36
	v_mov_b32_e32 v151, 0
	global_load_lds_dwordx4 v148, s[10:11]
	s_mov_b32 m0, s37
	s_lshr_b32 s19, s3, 8
	global_load_lds_dwordx4 v152, s[10:11]
	v_mov_b32_e32 v155, v151
	v_mov_b32_e32 v149, v151
	v_mov_b32_e32 v153, v151
	s_cmp_eq_u32 s19, 1
	s_mov_b32 s38, 0
	v_lshl_add_u64 v[0:1], s[4:5], 0, v[150:151]
	v_lshl_add_u64 v[2:3], s[4:5], 0, v[154:155]
	v_lshl_add_u64 v[4:5], s[6:7], 0, v[148:149]
	s_cselect_b64 s[8:9], -1, 0
	s_cmp_lg_u32 s19, 1
	v_lshl_add_u64 v[6:7], s[6:7], 0, v[152:153]
	s_cbranch_scc1 .LBB0_525
	s_barrier
